# scan step 3 scores: all fragment LDS reads issued up front (counted waits)
# speedup vs baseline: 1.0218x; 1.0050x over previous
.LBB0_314:
	v_mov_b32_e32 v135, v184
	v_add_u32_e32 v209, v183, v200
	ds_read_b128 v[102:105], v209 offset:12288
	v_lshlrev_b32_e32 v210, 7, v135
	v_add_u32_e32 v2, 16, v210
	v_add_u32_e32 v90, v2, v200
	ds_read_b128 v[90:93], v90
	v_add_u32_e32 v2, v2, v201
	ds_read_b128 v[94:97], v209 offset:8192
	ds_read_b128 v[98:101], v209 offset:10240
	ds_read_b128 v[236:239], v209 offset:14336
	ds_read_b128 v[216:219], v2
	v_add_u32_e32 v2, v183, v201
	ds_read_b128 v[220:223], v2 offset:8192
	ds_read_b128 v[224:227], v2 offset:10240
	ds_read_b128 v[228:231], v2 offset:12288
	ds_read_b128 v[232:235], v2 offset:14336
	s_waitcnt lgkmcnt(8)
	v_mfma_f32_16x16x32_bf16 v[212:215], v[102:105], v[90:93], 0
	s_waitcnt lgkmcnt(7)
	v_mfma_f32_16x16x32_bf16 v[94:97], v[94:97], v[90:93], 0
	s_waitcnt lgkmcnt(6)
	v_mfma_f32_16x16x32_bf16 v[98:101], v[98:101], v[90:93], 0
	s_waitcnt lgkmcnt(5)
	v_mfma_f32_16x16x32_bf16 v[90:93], v[236:239], v[90:93], 0
	s_waitcnt lgkmcnt(3)
	v_mfma_f32_16x16x32_bf16 v[102:105], v[220:223], v[216:219], v[94:97]
	s_waitcnt lgkmcnt(2)
	v_mfma_f32_16x16x32_bf16 v[98:101], v[224:227], v[216:219], v[98:101]
	s_waitcnt lgkmcnt(1)
	v_mfma_f32_16x16x32_bf16 v[94:97], v[228:231], v[216:219], v[212:215]
	s_waitcnt lgkmcnt(0)
	v_mfma_f32_16x16x32_bf16 v[90:93], v[232:235], v[216:219], v[90:93]
	s_and_saveexec_b64 s[0:1], s[22:23]
	s_xor_b64 s[0:1], exec, s[0:1]
	s_cbranch_execz .LBB0_318
	v_mov_b32_e32 v211, 0
	v_mov_b32_e32 v212, 0
	v_mov_b32_e32 v213, 0
	v_mov_b32_e32 v214, 0
	s_and_saveexec_b64 s[60:61], s[16:17]
	s_cbranch_execz .LBB0_317
	v_sub_u32_e32 v211, v142, v135
	v_mul_lo_u32 v212, v211, s39
	v_cmp_gt_i32_e32 vcc, 1, v212
	s_nop 1
	v_cndmask_b32_e32 v211, 0, v102, vcc
	v_add_u32_e32 v102, s39, v212
	v_cmp_gt_i32_e32 vcc, 1, v102
	v_add_u32_e32 v102, s39, v102
	s_nop 0
	v_cndmask_b32_e32 v212, 0, v103, vcc
	v_cmp_gt_i32_e32 vcc, 1, v102
	v_add_u32_e32 v102, s39, v102
	s_nop 0
	v_cndmask_b32_e32 v213, 0, v104, vcc
	v_cmp_gt_i32_e32 vcc, 1, v102
	s_nop 1
	v_cndmask_b32_e32 v214, 0, v105, vcc
